# combo1 + stick-breaking log(1+e): removed provably-dead denormal/inf handling around v_log (bit-identical outputs)
# baseline (speedup 1.0000x reference)
.LBB0_791:
	s_add_i32 s16, s6, 0x60
	s_cmp_le_i32 s16, s18
	s_cselect_b64 s[16:17], -1, 0
	v_add_u32_e32 v32, s33, v97
	v_add_u32_e32 v33, s33, v88
	s_and_b64 s[16:17], s[16:17], s[14:15]
	s_andn2_b64 vcc, exec, s[16:17]
	v_add_u32_e32 v82, v32, v112
	v_add_u32_e32 v81, s6, v96
	v_add_u32_e32 v80, v33, v111
	s_cbranch_vccnz .LBB0_793
	ds_read_b128 v[32:35], v82 offset:4608
	ds_read_b128 v[84:87], v82 offset:4640
	ds_read_b128 v[106:109], v82 offset:4672
	ds_read_b128 v[120:123], v82 offset:4704
	s_setprio 1
	s_waitcnt lgkmcnt(0)
	v_mfma_f32_32x32x16_bf16 v[32:47], v[32:35], v[64:67], 0
	v_mfma_f32_32x32x16_bf16 v[32:47], v[84:87], v[68:71], v[32:47]
	v_mfma_f32_32x32x16_bf16 v[32:47], v[106:109], v[72:75], v[32:47]
	v_mfma_f32_32x32x16_bf16 v[32:47], v[120:123], v[76:79], v[32:47]
	s_setprio 0
	s_nop 10
	v_mul_f32_e32 v60, 0x3e000000, v32
	v_mul_f32_e64 v61, |v60|, s37
	v_exp_f32_e32 v61, v61
	v_mul_f32_e32 v84, 0x3e000000, v33
	v_add_u32_e32 v62, 0x60, v81
	v_max_f32_e32 v60, 0, v60
	v_add_f32_e32 v61, 1.0, v61
	s_nop 1
	v_log_f32_e32 v61, v61
	s_nop 0
	v_mul_f32_e32 v85, 0x3f317217, v61
	v_fma_f32 v85, v61, s83, -v85
	v_fmac_f32_e32 v85, 0x3377d1cf, v61
	v_fmac_f32_e32 v85, 0x3f317217, v61
	s_nop 1
	v_mov_b32_e32 v61, v85
	v_mul_f32_e64 v83, |v84|, s37
	v_exp_f32_e32 v83, v83
	v_cmp_lt_i32_e32 vcc, v62, v102
	v_add_f32_e32 v61, v60, v61
	v_fma_f32 v32, v32, s81, -v61
	v_add_f32_e32 v62, 1.0, v83
	v_cndmask_b32_e64 v60, 0, -v61, vcc
	s_nop 0
	v_log_f32_e32 v62, v62
	s_nop 0
	v_cndmask_b32_e32 v83, v212, v32, vcc
	v_max_f32_e32 v32, 0, v84
	v_mul_f32_e32 v61, 0x3f317217, v62
	v_fma_f32 v61, v62, s83, -v61
	v_fmac_f32_e32 v61, 0x3377d1cf, v62
	v_fmac_f32_e32 v61, 0x3f317217, v62
	s_nop 1
	v_mul_f32_e32 v62, 0x3e000000, v34
	v_add_f32_e32 v61, v32, v61
	v_mul_f32_e64 v32, |v62|, s37
	v_exp_f32_e32 v84, v32
	v_add_u32_e32 v32, 0x61, v81
	v_cmp_lt_i32_e32 vcc, v32, v102
	v_fma_f32 v33, v33, s81, -v61
	v_add_f32_e32 v84, 1.0, v84
	v_cndmask_b32_e64 v32, 0, -v61, vcc
	s_nop 0
	v_log_f32_e32 v85, v84
	s_nop 0
	v_cndmask_b32_e32 v84, v212, v33, vcc
	v_max_f32_e32 v33, 0, v62
	v_mul_f32_e32 v61, 0x3f317217, v85
	v_fma_f32 v61, v85, s83, -v61
	v_fmac_f32_e32 v61, 0x3377d1cf, v85
	v_fmac_f32_e32 v61, 0x3f317217, v85
	s_nop 1
	v_add_f32_e32 v33, v33, v61
	v_mul_f32_e32 v61, 0x3e000000, v35
	v_mul_f32_e64 v62, |v61|, s37
	v_exp_f32_e32 v85, v62
	v_add_u32_e32 v62, 0x62, v81
	v_cmp_lt_i32_e32 vcc, v62, v102
	v_add_f32_e32 v85, 1.0, v85
	v_cndmask_b32_e64 v62, 0, -v33, vcc
	v_fma_f32 v33, v34, s81, -v33
	v_log_f32_e32 v85, v85
	s_nop 0
	v_cndmask_b32_e32 v86, v212, v33, vcc
	v_max_f32_e32 v33, 0, v61
	v_mul_f32_e32 v34, 0x3f317217, v85
	v_fma_f32 v34, v85, s83, -v34
	v_fmac_f32_e32 v34, 0x3377d1cf, v85
	v_fmac_f32_e32 v34, 0x3f317217, v85
	s_nop 1
	v_mul_f32_e32 v61, 0x3e000000, v36
	v_add_f32_e32 v33, v33, v34
	v_mul_f32_e64 v34, |v61|, s37
	v_exp_f32_e32 v85, v34
	v_add_u32_e32 v34, 0x63, v81
	v_cmp_lt_i32_e32 vcc, v34, v102
	v_add_f32_e32 v85, 1.0, v85
	v_cndmask_b32_e64 v34, 0, -v33, vcc
	v_fma_f32 v33, v35, s81, -v33
	v_log_f32_e32 v85, v85
	s_nop 0
	v_cndmask_b32_e32 v87, v212, v33, vcc
	v_max_f32_e32 v33, 0, v61
	v_mul_f32_e32 v35, 0x3f317217, v85
	v_fma_f32 v35, v85, s83, -v35
	v_fmac_f32_e32 v35, 0x3377d1cf, v85
	v_fmac_f32_e32 v35, 0x3f317217, v85
	s_nop 1
	v_add_f32_e32 v33, v33, v35
	v_mul_f32_e32 v35, 0x3e000000, v37
	v_mul_f32_e64 v61, |v35|, s37
	v_exp_f32_e32 v61, v61
	v_add_u32_e32 v85, 0x68, v81
	v_cmp_lt_i32_e32 vcc, v85, v102
	v_add_f32_e32 v61, 1.0, v61
	v_cndmask_b32_e64 v85, 0, -v33, vcc
	v_fma_f32 v33, v36, s81, -v33
	v_log_f32_e32 v61, v61
	s_nop 0
	v_cndmask_b32_e32 v99, v212, v33, vcc
	v_max_f32_e32 v33, 0, v35
	v_mul_f32_e32 v35, 0x3f317217, v61
	v_fma_f32 v35, v61, s83, -v35
	v_fmac_f32_e32 v35, 0x3377d1cf, v61
	v_fmac_f32_e32 v35, 0x3f317217, v61
	s_nop 1
	v_add_f32_e32 v33, v33, v35
	v_mul_f32_e32 v35, 0x3e000000, v38
	v_mul_f32_e64 v36, |v35|, s37
	v_exp_f32_e32 v36, v36
	v_add_u32_e32 v61, 0x69, v81
	v_cmp_lt_i32_e32 vcc, v61, v102
	v_add_f32_e32 v36, 1.0, v36
	v_cndmask_b32_e64 v103, 0, -v33, vcc
	v_fma_f32 v33, v37, s81, -v33
	v_log_f32_e32 v36, v36
	s_nop 0
	v_cndmask_b32_e32 v105, v212, v33, vcc
	v_max_f32_e32 v33, 0, v35
	v_add_u32_e32 v37, 0x6a, v81
	v_mul_f32_e32 v35, 0x3f317217, v36
	v_fma_f32 v35, v36, s83, -v35
	v_fmac_f32_e32 v35, 0x3377d1cf, v36
	v_fmac_f32_e32 v35, 0x3f317217, v36
	s_nop 1
	v_add_f32_e32 v33, v33, v35
	v_mul_f32_e32 v35, 0x3e000000, v39
	v_mul_f32_e64 v36, |v35|, s37
	v_exp_f32_e32 v36, v36
	v_cmp_lt_i32_e32 vcc, v37, v102
	v_add_f32_e32 v36, 1.0, v36
	v_cndmask_b32_e64 v106, 0, -v33, vcc
	v_fma_f32 v33, v38, s81, -v33
	v_log_f32_e32 v36, v36
	s_nop 0
	v_cndmask_b32_e32 v107, v212, v33, vcc
	v_max_f32_e32 v33, 0, v35
	v_add_u32_e32 v37, 0x6b, v81
	v_mul_f32_e32 v35, 0x3f317217, v36
	v_fma_f32 v35, v36, s83, -v35
	v_fmac_f32_e32 v35, 0x3377d1cf, v36
	v_fmac_f32_e32 v35, 0x3f317217, v36
	s_nop 1
	v_add_f32_e32 v33, v33, v35
	v_mul_f32_e32 v35, 0x3e000000, v40
	v_mul_f32_e64 v36, |v35|, s37
	v_exp_f32_e32 v36, v36
	v_cmp_lt_i32_e32 vcc, v37, v102
	v_add_f32_e32 v36, 1.0, v36
	v_cndmask_b32_e64 v108, 0, -v33, vcc
	v_fma_f32 v33, v39, s81, -v33
	v_log_f32_e32 v36, v36
	s_nop 0
	v_cndmask_b32_e32 v109, v212, v33, vcc
	v_max_f32_e32 v33, 0, v35
	v_add_u32_e32 v37, 0x70, v81
	v_mul_f32_e32 v35, 0x3f317217, v36
	v_fma_f32 v35, v36, s83, -v35
	v_fmac_f32_e32 v35, 0x3377d1cf, v36
	v_fmac_f32_e32 v35, 0x3f317217, v36
	v_add_u32_e32 v39, 0x71, v81
	s_nop 0
	v_add_f32_e32 v33, v33, v35
	v_mul_f32_e32 v35, 0x3e000000, v41
	v_mul_f32_e64 v36, |v35|, s37
	v_exp_f32_e32 v36, v36
	v_cmp_lt_i32_e32 vcc, v37, v102
	v_add_f32_e32 v36, 1.0, v36
	v_cndmask_b32_e64 v37, 0, -v33, vcc
	v_fma_f32 v33, v40, s81, -v33
	v_log_f32_e32 v36, v36
	s_nop 0
	v_cndmask_b32_e32 v38, v212, v33, vcc
	v_max_f32_e32 v33, 0, v35
	v_mul_f32_e32 v35, 0x3f317217, v36
	v_fma_f32 v35, v36, s83, -v35
	v_fmac_f32_e32 v35, 0x3377d1cf, v36
	v_fmac_f32_e32 v35, 0x3f317217, v36
	s_nop 1
	v_add_f32_e32 v33, v33, v35
	v_mul_f32_e32 v35, 0x3e000000, v42
	v_mul_f32_e64 v36, |v35|, s37
	v_exp_f32_e32 v36, v36
	v_cmp_lt_i32_e32 vcc, v39, v102
	v_add_f32_e32 v36, 1.0, v36
	v_cndmask_b32_e64 v39, 0, -v33, vcc
	v_fma_f32 v33, v41, s81, -v33
	v_log_f32_e32 v36, v36
	s_nop 0
	v_cndmask_b32_e32 v40, v212, v33, vcc
	v_max_f32_e32 v33, 0, v35
	v_add_u32_e32 v41, 0x72, v81
	v_mul_f32_e32 v35, 0x3f317217, v36
	v_fma_f32 v35, v36, s83, -v35
	v_fmac_f32_e32 v35, 0x3377d1cf, v36
	v_fmac_f32_e32 v35, 0x3f317217, v36
	v_add_f32_e32 v37, v37, v39
	s_nop 0
	v_add_f32_e32 v33, v33, v35
	v_mul_f32_e32 v35, 0x3e000000, v43
	v_mul_f32_e64 v36, |v35|, s37
	v_exp_f32_e32 v36, v36
	v_cmp_lt_i32_e32 vcc, v41, v102
	v_add_f32_e32 v36, 1.0, v36
	v_cndmask_b32_e64 v41, 0, -v33, vcc
	v_fma_f32 v33, v42, s81, -v33
	v_log_f32_e32 v36, v36
	s_nop 0
	v_cndmask_b32_e32 v42, v212, v33, vcc
	v_max_f32_e32 v33, 0, v35
	v_add_u32_e32 v61, 0x73, v81
	v_mul_f32_e32 v35, 0x3f317217, v36
	v_fma_f32 v35, v36, s83, -v35
	v_fmac_f32_e32 v35, 0x3377d1cf, v36
	v_fmac_f32_e32 v35, 0x3f317217, v36
	s_nop 1
	v_add_f32_e32 v33, v33, v35
	v_mul_f32_e32 v35, 0x3e000000, v44
	v_mul_f32_e64 v36, |v35|, s37
	v_exp_f32_e32 v36, v36
	v_cmp_lt_i32_e32 vcc, v61, v102
	v_add_f32_e32 v36, 1.0, v36
	v_cndmask_b32_e64 v120, 0, -v33, vcc
	v_fma_f32 v33, v43, s81, -v33
	v_log_f32_e32 v36, v36
	s_nop 0
	v_cndmask_b32_e32 v43, v212, v33, vcc
	v_max_f32_e32 v33, 0, v35
	v_add_u32_e32 v61, 0x78, v81
	v_mul_f32_e32 v35, 0x3f317217, v36
	v_fma_f32 v35, v36, s83, -v35
	v_fmac_f32_e32 v35, 0x3377d1cf, v36
	v_fmac_f32_e32 v35, 0x3f317217, v36
	s_nop 1
	v_add_f32_e32 v33, v33, v35
	v_mul_f32_e32 v35, 0x3e000000, v45
	v_mul_f32_e64 v36, |v35|, s37
	v_exp_f32_e32 v36, v36
	v_cmp_lt_i32_e32 vcc, v61, v102
	v_add_f32_e32 v36, 1.0, v36
	v_cndmask_b32_e64 v121, 0, -v33, vcc
	v_fma_f32 v33, v44, s81, -v33
	v_log_f32_e32 v36, v36
	s_nop 0
	v_cndmask_b32_e32 v44, v212, v33, vcc
	v_max_f32_e32 v33, 0, v35
	v_add_u32_e32 v61, 0x79, v81
	v_mul_f32_e32 v35, 0x3f317217, v36
	v_fma_f32 v35, v36, s83, -v35
	v_fmac_f32_e32 v35, 0x3377d1cf, v36
	v_fmac_f32_e32 v35, 0x3f317217, v36
	s_nop 1
	v_add_f32_e32 v33, v33, v35
	v_mul_f32_e32 v35, 0x3e000000, v46
	v_mul_f32_e64 v36, |v35|, s37
	v_exp_f32_e32 v36, v36
	v_cmp_lt_i32_e32 vcc, v61, v102
	v_add_f32_e32 v36, 1.0, v36
	v_cndmask_b32_e64 v122, 0, -v33, vcc
	v_fma_f32 v33, v45, s81, -v33
	v_log_f32_e32 v36, v36
	s_nop 0
	v_cndmask_b32_e32 v45, v212, v33, vcc
	v_max_f32_e32 v33, 0, v35
	v_add_u32_e32 v61, 0x7a, v81
	v_mul_f32_e32 v35, 0x3f317217, v36
	v_fma_f32 v35, v36, s83, -v35
	v_fmac_f32_e32 v35, 0x3377d1cf, v36
	v_fmac_f32_e32 v35, 0x3f317217, v36
	s_nop 1
	v_add_f32_e32 v33, v33, v35
	v_mul_f32_e32 v35, 0x3e000000, v47
	v_mul_f32_e64 v36, |v35|, s37
	v_exp_f32_e32 v36, v36
	v_cmp_lt_i32_e32 vcc, v61, v102
	v_add_f32_e32 v36, 1.0, v36
	v_cndmask_b32_e64 v123, 0, -v33, vcc
	v_fma_f32 v33, v46, s81, -v33
	v_log_f32_e32 v36, v36
	s_nop 0
	v_cndmask_b32_e32 v46, v212, v33, vcc
	v_max_f32_e32 v33, 0, v35
	v_mul_f32_e32 v35, 0x3f317217, v36
	v_fma_f32 v35, v36, s83, -v35
	v_fmac_f32_e32 v35, 0x3377d1cf, v36
	v_fmac_f32_e32 v35, 0x3f317217, v36
	s_nop 1
	v_add_f32_e32 v33, v33, v35
	v_add_u32_e32 v35, 0x7b, v81
	v_cmp_lt_i32_e32 vcc, v35, v102
	s_nop 1
	v_cndmask_b32_e64 v35, 0, -v33, vcc
	v_fma_f32 v33, v47, s81, -v33
	v_cndmask_b32_e32 v36, v212, v33, vcc
	v_add_f32_e32 v33, v85, v103
	v_add_f32_e32 v47, v106, v108
	v_add_f32_e32 v61, v33, v47
	v_add_f32_e32 v47, v121, v122
	v_add_f32_e32 v85, v123, v35
	v_add_f32_e32 v47, v47, v85
	ds_bpermute_b32 v85, v110, v47
	v_add_f32_e32 v121, v41, v120
	v_add_f32_e32 v37, v37, v121
	ds_bpermute_b32 v121, v110, v37
	ds_bpermute_b32 v33, v110, v61
	s_waitcnt lgkmcnt(0)
	v_cndmask_b32_e64 v124, 0, v85, s[52:53]
	v_add_f32_e32 v124, v63, v124
	v_add_f32_e32 v36, v124, v36
	v_mul_f32_e32 v36, 0x3fb8aa3b, v36
	v_add_f32_e32 v35, v124, v35
	v_exp_f32_e32 v125, v36
	v_add_f32_e32 v36, v46, v35
	v_mul_f32_e32 v36, 0x3fb8aa3b, v36
	v_add_f32_e32 v35, v123, v35
	v_exp_f32_e32 v124, v36
	v_add_f32_e32 v36, v45, v35
	v_add_f32_e32 v35, v122, v35
	v_add_f32_e32 v35, v44, v35
	v_mul_f32_e32 v35, 0x3fb8aa3b, v35
	v_mul_f32_e32 v36, 0x3fb8aa3b, v36
	v_exp_f32_e32 v122, v35
	v_add_f32_e32 v35, v47, v85
	v_exp_f32_e32 v46, v36
	v_add_f32_e32 v35, v63, v35
	v_cndmask_b32_e64 v36, 0, v121, s[52:53]
	v_add_f32_e32 v36, v36, v35
	v_add_f32_e32 v43, v43, v36
	v_add_f32_e32 v36, v120, v36
	v_add_f32_e32 v42, v42, v36
	v_add_f32_e32 v36, v41, v36
	v_add_f32_e32 v40, v40, v36
	v_add_f32_e32 v36, v39, v36
	v_add_f32_e32 v36, v38, v36
	v_mul_f32_e32 v36, 0x3fb8aa3b, v36
	v_add_f32_e32 v63, v37, v121
	v_exp_f32_e32 v85, v36
	v_pk_add_f32 v[36:37], v[62:63], v[34:35]
	v_pk_add_f32 v[38:39], v[60:61], v[32:33]
	v_mul_f32_e32 v40, 0x3fb8aa3b, v40
	v_pk_add_f32 v[38:39], v[38:39], v[36:37]
	v_exp_f32_e32 v44, v40
	v_cndmask_b32_e64 v40, 0, v33, s[52:53]
	ds_bpermute_b32 v33, v110, v38
	v_add_f32_e32 v35, v40, v37
	v_add_f32_e32 v36, v109, v35
	v_add_f32_e32 v35, v108, v35
	v_mul_f32_e32 v42, 0x3fb8aa3b, v42
	s_waitcnt lgkmcnt(0)
	v_cndmask_b32_e64 v41, 0, v33, s[52:53]
	v_add_f32_e32 v41, v41, v39
	v_add_f32_e32 v37, v107, v35
	v_add_f32_e32 v35, v106, v35
	v_add_f32_e32 v34, v34, v41
	v_exp_f32_e32 v47, v42
	v_add_f32_e32 v40, v105, v35
	v_add_f32_e32 v35, v103, v35
	v_add_f32_e32 v42, v87, v41
	v_add_f32_e32 v41, v86, v34
	v_add_f32_e32 v34, v62, v34
	v_mul_f32_e32 v43, 0x3fb8aa3b, v43
	v_add_f32_e32 v35, v99, v35
	v_add_f32_e32 v32, v32, v34
	v_exp_f32_e32 v45, v43
	v_mul_f32_e32 v40, 0x3fb8aa3b, v40
	v_mul_f32_e32 v35, 0x3fb8aa3b, v35
	v_mul_f32_e32 v42, 0x3fb8aa3b, v42
	v_mul_f32_e32 v41, 0x3fb8aa3b, v41
	v_add_f32_e32 v43, v84, v34
	v_add_f32_e32 v32, v83, v32
	v_mul_f32_e32 v36, 0x3fb8aa3b, v36
	v_mul_f32_e32 v37, 0x3fb8aa3b, v37
	v_exp_f32_e32 v40, v40
	v_exp_f32_e32 v35, v35
	v_exp_f32_e32 v42, v42
	v_mul_f32_e32 v43, 0x3fb8aa3b, v43
	v_mul_f32_e32 v32, 0x3fb8aa3b, v32
	v_exp_f32_e32 v34, v41
	v_exp_f32_e32 v36, v36
	v_exp_f32_e32 v37, v37
	v_exp_f32_e32 v43, v43
	v_exp_f32_e32 v32, v32
	v_add_f32_e32 v33, v38, v33
	v_add_f32_e32 v63, v33, v39
	v_cvt_pk_bf16_f32 v33, v34, v42
	v_cvt_pk_bf16_f32 v34, v35, v40
	v_add_u32_e32 v40, 0x2000, v80
	v_cvt_pk_bf16_f32 v32, v32, v43
	v_cvt_pk_bf16_f32 v35, v37, v36
	ds_read2_b64 v[36:39], v40 offset0:136 offset1:138
	ds_read2_b64 v[40:43], v40 offset0:140 offset1:142
	v_cvt_pk_bf16_f32 v44, v85, v44
	v_cvt_pk_bf16_f32 v45, v47, v45
	v_cvt_pk_bf16_f32 v46, v122, v46
	v_cvt_pk_bf16_f32 v47, v124, v125
	s_setprio 1
	s_waitcnt lgkmcnt(0)
	v_mfma_f32_32x32x16_bf16 v[16:31], v[36:39], v[32:35], v[16:31]
	v_mfma_f32_32x32x16_bf16 v[16:31], v[40:43], v[44:47], v[16:31]
	s_setprio 0
	v_add_u32_e32 v40, 0x3000, v80
	ds_read2_b64 v[36:39], v40 offset0:168 offset1:170
	ds_read2_b64 v[40:43], v40 offset0:172 offset1:174
	s_setprio 1
	s_waitcnt lgkmcnt(0)
	v_mfma_f32_32x32x16_bf16 v[0:15], v[36:39], v[32:35], v[0:15]
	v_mfma_f32_32x32x16_bf16 v[0:15], v[40:43], v[44:47], v[0:15]
	s_setprio 0
	v_cmp_gt_f32_e32 vcc, s5, v63
	s_cmp_lg_u64 vcc, exec
	s_cselect_b64 s[14:15], -1, 0
.LBB0_793:
	s_add_i32 s16, s6, 64
	s_cmp_le_i32 s16, s18
	s_cselect_b64 s[16:17], -1, 0
	s_and_b64 s[16:17], s[16:17], s[14:15]
	s_andn2_b64 vcc, exec, s[16:17]
	s_cbranch_vccnz .LBB0_795
	ds_read_b128 v[32:35], v82
	ds_read_b128 v[84:87], v82 offset:32
	ds_read_b128 v[106:109], v82 offset:64
	ds_read_b128 v[120:123], v82 offset:96
	s_setprio 1
	s_waitcnt lgkmcnt(0)
	v_mfma_f32_32x32x16_bf16 v[32:47], v[32:35], v[64:67], 0
	v_mfma_f32_32x32x16_bf16 v[32:47], v[84:87], v[68:71], v[32:47]
	v_mfma_f32_32x32x16_bf16 v[32:47], v[106:109], v[72:75], v[32:47]
	v_mfma_f32_32x32x16_bf16 v[32:47], v[120:123], v[76:79], v[32:47]
	s_setprio 0
	s_nop 10
	v_mul_f32_e32 v60, 0x3e000000, v32
	v_mul_f32_e64 v61, |v60|, s37
	v_exp_f32_e32 v61, v61
	v_mul_f32_e32 v83, 0x3e000000, v33
	v_add_u32_e32 v62, 64, v81
	v_max_f32_e32 v60, 0, v60
	v_add_f32_e32 v61, 1.0, v61
	s_nop 1
	v_log_f32_e32 v61, v61
	s_nop 0
	v_mul_f32_e32 v84, 0x3f317217, v61
	v_fma_f32 v84, v61, s83, -v84
	v_fmac_f32_e32 v84, 0x3377d1cf, v61
	v_fmac_f32_e32 v84, 0x3f317217, v61
	s_nop 1
	v_mov_b32_e32 v61, v84
	v_mul_f32_e64 v82, |v83|, s37
	v_exp_f32_e32 v82, v82
	v_cmp_lt_i32_e32 vcc, v62, v102
	v_add_f32_e32 v61, v60, v61
	v_fma_f32 v32, v32, s81, -v61
	v_add_f32_e32 v62, 1.0, v82
	v_cndmask_b32_e64 v60, 0, -v61, vcc
	s_nop 0
	v_log_f32_e32 v62, v62
	s_nop 0
	v_cndmask_b32_e32 v82, v212, v32, vcc
	v_max_f32_e32 v32, 0, v83
	v_mul_f32_e32 v61, 0x3f317217, v62
	v_fma_f32 v61, v62, s83, -v61
	v_fmac_f32_e32 v61, 0x3377d1cf, v62
	v_fmac_f32_e32 v61, 0x3f317217, v62
	s_nop 1
	v_mul_f32_e32 v62, 0x3e000000, v34
	v_add_f32_e32 v61, v32, v61
	v_mul_f32_e64 v32, |v62|, s37
	v_exp_f32_e32 v83, v32
	v_add_u32_e32 v32, 0x41, v81
	v_cmp_lt_i32_e32 vcc, v32, v102
	v_fma_f32 v33, v33, s81, -v61
	v_add_f32_e32 v83, 1.0, v83
	v_cndmask_b32_e64 v32, 0, -v61, vcc
	s_nop 0
	v_log_f32_e32 v84, v83
	s_nop 0
	v_cndmask_b32_e32 v83, v212, v33, vcc
	v_max_f32_e32 v33, 0, v62
	v_mul_f32_e32 v61, 0x3f317217, v84
	v_fma_f32 v61, v84, s83, -v61
	v_fmac_f32_e32 v61, 0x3377d1cf, v84
	v_fmac_f32_e32 v61, 0x3f317217, v84
	s_nop 1
	v_add_f32_e32 v33, v33, v61
	v_mul_f32_e32 v61, 0x3e000000, v35
	v_mul_f32_e64 v62, |v61|, s37
	v_exp_f32_e32 v84, v62
	v_add_u32_e32 v62, 0x42, v81
	v_cmp_lt_i32_e32 vcc, v62, v102
	v_add_f32_e32 v84, 1.0, v84
	v_cndmask_b32_e64 v62, 0, -v33, vcc
	v_fma_f32 v33, v34, s81, -v33
	v_log_f32_e32 v84, v84
	s_nop 0
	v_cndmask_b32_e32 v85, v212, v33, vcc
	v_max_f32_e32 v33, 0, v61
	v_mul_f32_e32 v34, 0x3f317217, v84
	v_fma_f32 v34, v84, s83, -v34
	v_fmac_f32_e32 v34, 0x3377d1cf, v84
	v_fmac_f32_e32 v34, 0x3f317217, v84
	s_nop 1
	v_mul_f32_e32 v61, 0x3e000000, v36
	v_add_f32_e32 v33, v33, v34
	v_mul_f32_e64 v34, |v61|, s37
	v_exp_f32_e32 v84, v34
	v_add_u32_e32 v34, 0x43, v81
	v_cmp_lt_i32_e32 vcc, v34, v102
	v_add_f32_e32 v84, 1.0, v84
	v_cndmask_b32_e64 v34, 0, -v33, vcc
	v_fma_f32 v33, v35, s81, -v33
	v_log_f32_e32 v84, v84
	s_nop 0
	v_cndmask_b32_e32 v86, v212, v33, vcc
	v_max_f32_e32 v33, 0, v61
	v_mul_f32_e32 v35, 0x3f317217, v84
	v_fma_f32 v35, v84, s83, -v35
	v_fmac_f32_e32 v35, 0x3377d1cf, v84
	v_fmac_f32_e32 v35, 0x3f317217, v84
	s_nop 1
	v_add_f32_e32 v33, v33, v35
	v_mul_f32_e32 v35, 0x3e000000, v37
	v_mul_f32_e64 v61, |v35|, s37
	v_exp_f32_e32 v61, v61
	v_add_u32_e32 v84, 0x48, v81
	v_cmp_lt_i32_e32 vcc, v84, v102
	v_add_f32_e32 v61, 1.0, v61
	v_cndmask_b32_e64 v84, 0, -v33, vcc
	v_fma_f32 v33, v36, s81, -v33
	v_log_f32_e32 v61, v61
	s_nop 0
	v_cndmask_b32_e32 v87, v212, v33, vcc
	v_max_f32_e32 v33, 0, v35
	v_mul_f32_e32 v35, 0x3f317217, v61
	v_fma_f32 v35, v61, s83, -v35
	v_fmac_f32_e32 v35, 0x3377d1cf, v61
	v_fmac_f32_e32 v35, 0x3f317217, v61
	s_nop 1
	v_add_f32_e32 v33, v33, v35
	v_mul_f32_e32 v35, 0x3e000000, v38
	v_mul_f32_e64 v36, |v35|, s37
	v_exp_f32_e32 v36, v36
	v_add_u32_e32 v61, 0x49, v81
	v_cmp_lt_i32_e32 vcc, v61, v102
	v_add_f32_e32 v36, 1.0, v36
	v_cndmask_b32_e64 v99, 0, -v33, vcc
	v_fma_f32 v33, v37, s81, -v33
	v_log_f32_e32 v36, v36
	s_nop 0
	v_cndmask_b32_e32 v103, v212, v33, vcc
	v_max_f32_e32 v33, 0, v35
	v_add_u32_e32 v37, 0x4a, v81
	v_mul_f32_e32 v35, 0x3f317217, v36
	v_fma_f32 v35, v36, s83, -v35
	v_fmac_f32_e32 v35, 0x3377d1cf, v36
	v_fmac_f32_e32 v35, 0x3f317217, v36
	s_nop 1
	v_add_f32_e32 v33, v33, v35
	v_mul_f32_e32 v35, 0x3e000000, v39
	v_mul_f32_e64 v36, |v35|, s37
	v_exp_f32_e32 v36, v36
	v_cmp_lt_i32_e32 vcc, v37, v102
	v_add_f32_e32 v36, 1.0, v36
	v_cndmask_b32_e64 v105, 0, -v33, vcc
	v_fma_f32 v33, v38, s81, -v33
	v_log_f32_e32 v36, v36
	s_nop 0
	v_cndmask_b32_e32 v106, v212, v33, vcc
	v_max_f32_e32 v33, 0, v35
	v_add_u32_e32 v37, 0x4b, v81
	v_mul_f32_e32 v35, 0x3f317217, v36
	v_fma_f32 v35, v36, s83, -v35
	v_fmac_f32_e32 v35, 0x3377d1cf, v36
	v_fmac_f32_e32 v35, 0x3f317217, v36
	s_nop 1
	v_add_f32_e32 v33, v33, v35
	v_mul_f32_e32 v35, 0x3e000000, v40
	v_mul_f32_e64 v36, |v35|, s37
	v_exp_f32_e32 v36, v36
	v_cmp_lt_i32_e32 vcc, v37, v102
	v_add_f32_e32 v36, 1.0, v36
	v_cndmask_b32_e64 v107, 0, -v33, vcc
	v_fma_f32 v33, v39, s81, -v33
	v_log_f32_e32 v36, v36
	s_nop 0
	v_cndmask_b32_e32 v108, v212, v33, vcc
	v_max_f32_e32 v33, 0, v35
	v_add_u32_e32 v37, 0x50, v81
	v_mul_f32_e32 v35, 0x3f317217, v36
	v_fma_f32 v35, v36, s83, -v35
	v_fmac_f32_e32 v35, 0x3377d1cf, v36
	v_fmac_f32_e32 v35, 0x3f317217, v36
	v_add_u32_e32 v39, 0x51, v81
	s_nop 0
	v_add_f32_e32 v33, v33, v35
	v_mul_f32_e32 v35, 0x3e000000, v41
	v_mul_f32_e64 v36, |v35|, s37
	v_exp_f32_e32 v36, v36
	v_cmp_lt_i32_e32 vcc, v37, v102
	v_add_f32_e32 v36, 1.0, v36
	v_cndmask_b32_e64 v37, 0, -v33, vcc
	v_fma_f32 v33, v40, s81, -v33
	v_log_f32_e32 v36, v36
	s_nop 0
	v_cndmask_b32_e32 v38, v212, v33, vcc
	v_max_f32_e32 v33, 0, v35
	v_mul_f32_e32 v35, 0x3f317217, v36
	v_fma_f32 v35, v36, s83, -v35
	v_fmac_f32_e32 v35, 0x3377d1cf, v36
	v_fmac_f32_e32 v35, 0x3f317217, v36
	s_nop 1
	v_add_f32_e32 v33, v33, v35
	v_mul_f32_e32 v35, 0x3e000000, v42
	v_mul_f32_e64 v36, |v35|, s37
	v_exp_f32_e32 v36, v36
	v_cmp_lt_i32_e32 vcc, v39, v102
	v_add_f32_e32 v36, 1.0, v36
	v_cndmask_b32_e64 v39, 0, -v33, vcc
	v_fma_f32 v33, v41, s81, -v33
	v_log_f32_e32 v36, v36
	s_nop 0
	v_cndmask_b32_e32 v40, v212, v33, vcc
	v_max_f32_e32 v33, 0, v35
	v_add_u32_e32 v41, 0x52, v81
	v_mul_f32_e32 v35, 0x3f317217, v36
	v_fma_f32 v35, v36, s83, -v35
	v_fmac_f32_e32 v35, 0x3377d1cf, v36
	v_fmac_f32_e32 v35, 0x3f317217, v36
	v_add_f32_e32 v37, v37, v39
	s_nop 0
	v_add_f32_e32 v33, v33, v35
	v_mul_f32_e32 v35, 0x3e000000, v43
	v_mul_f32_e64 v36, |v35|, s37
	v_exp_f32_e32 v36, v36
	v_cmp_lt_i32_e32 vcc, v41, v102
	v_add_f32_e32 v36, 1.0, v36
	v_cndmask_b32_e64 v41, 0, -v33, vcc
	v_fma_f32 v33, v42, s81, -v33
	v_log_f32_e32 v36, v36
	s_nop 0
	v_cndmask_b32_e32 v42, v212, v33, vcc
	v_max_f32_e32 v33, 0, v35
	v_add_u32_e32 v61, 0x53, v81
	v_mul_f32_e32 v35, 0x3f317217, v36
	v_fma_f32 v35, v36, s83, -v35
	v_fmac_f32_e32 v35, 0x3377d1cf, v36
	v_fmac_f32_e32 v35, 0x3f317217, v36
	s_nop 1
	v_add_f32_e32 v33, v33, v35
	v_mul_f32_e32 v35, 0x3e000000, v44
	v_mul_f32_e64 v36, |v35|, s37
	v_exp_f32_e32 v36, v36
	v_cmp_lt_i32_e32 vcc, v61, v102
	v_add_f32_e32 v36, 1.0, v36
	v_cndmask_b32_e64 v109, 0, -v33, vcc
	v_fma_f32 v33, v43, s81, -v33
	v_log_f32_e32 v36, v36
	s_nop 0
	v_cndmask_b32_e32 v43, v212, v33, vcc
	v_max_f32_e32 v33, 0, v35
	v_add_u32_e32 v61, 0x58, v81
	v_mul_f32_e32 v35, 0x3f317217, v36
	v_fma_f32 v35, v36, s83, -v35
	v_fmac_f32_e32 v35, 0x3377d1cf, v36
	v_fmac_f32_e32 v35, 0x3f317217, v36
	s_nop 1
	v_add_f32_e32 v33, v33, v35
	v_mul_f32_e32 v35, 0x3e000000, v45
	v_mul_f32_e64 v36, |v35|, s37
	v_exp_f32_e32 v36, v36
	v_cmp_lt_i32_e32 vcc, v61, v102
	v_add_f32_e32 v36, 1.0, v36
	v_cndmask_b32_e64 v120, 0, -v33, vcc
	v_fma_f32 v33, v44, s81, -v33
	v_log_f32_e32 v36, v36
	s_nop 0
	v_cndmask_b32_e32 v44, v212, v33, vcc
	v_max_f32_e32 v33, 0, v35
	v_add_u32_e32 v61, 0x59, v81
	v_mul_f32_e32 v35, 0x3f317217, v36
	v_fma_f32 v35, v36, s83, -v35
	v_fmac_f32_e32 v35, 0x3377d1cf, v36
	v_fmac_f32_e32 v35, 0x3f317217, v36
	s_nop 1
	v_add_f32_e32 v33, v33, v35
	v_mul_f32_e32 v35, 0x3e000000, v46
	v_mul_f32_e64 v36, |v35|, s37
	v_exp_f32_e32 v36, v36
	v_cmp_lt_i32_e32 vcc, v61, v102
	v_add_f32_e32 v36, 1.0, v36
	v_cndmask_b32_e64 v121, 0, -v33, vcc
	v_fma_f32 v33, v45, s81, -v33
	v_log_f32_e32 v36, v36
	s_nop 0
	v_cndmask_b32_e32 v45, v212, v33, vcc
	v_max_f32_e32 v33, 0, v35
	v_add_u32_e32 v61, 0x5a, v81
	v_mul_f32_e32 v35, 0x3f317217, v36
	v_fma_f32 v35, v36, s83, -v35
	v_fmac_f32_e32 v35, 0x3377d1cf, v36
	v_fmac_f32_e32 v35, 0x3f317217, v36
	s_nop 1
	v_add_f32_e32 v33, v33, v35
	v_mul_f32_e32 v35, 0x3e000000, v47
	v_mul_f32_e64 v36, |v35|, s37
	v_exp_f32_e32 v36, v36
	v_cmp_lt_i32_e32 vcc, v61, v102
	v_add_f32_e32 v36, 1.0, v36
	v_cndmask_b32_e64 v122, 0, -v33, vcc
	v_fma_f32 v33, v46, s81, -v33
	v_log_f32_e32 v36, v36
	s_nop 0
	v_cndmask_b32_e32 v46, v212, v33, vcc
	v_max_f32_e32 v33, 0, v35
	v_mul_f32_e32 v35, 0x3f317217, v36
	v_fma_f32 v35, v36, s83, -v35
	v_fmac_f32_e32 v35, 0x3377d1cf, v36
	v_fmac_f32_e32 v35, 0x3f317217, v36
	s_nop 1
	v_add_f32_e32 v33, v33, v35
	v_add_u32_e32 v35, 0x5b, v81
	v_cmp_lt_i32_e32 vcc, v35, v102
	s_nop 1
	v_cndmask_b32_e64 v35, 0, -v33, vcc
	v_fma_f32 v33, v47, s81, -v33
	v_cndmask_b32_e32 v36, v212, v33, vcc
	v_add_f32_e32 v33, v84, v99
	v_add_f32_e32 v47, v105, v107
	v_add_f32_e32 v61, v33, v47
	v_add_f32_e32 v47, v120, v121
	v_add_f32_e32 v81, v122, v35
	v_add_f32_e32 v47, v47, v81
	ds_bpermute_b32 v81, v110, v47
	v_add_f32_e32 v84, v41, v109
	v_add_f32_e32 v37, v37, v84
	ds_bpermute_b32 v84, v110, v37
	ds_bpermute_b32 v33, v110, v61
	s_waitcnt lgkmcnt(0)
	v_cndmask_b32_e64 v120, 0, v81, s[52:53]
	v_add_f32_e32 v120, v63, v120
	v_add_f32_e32 v36, v120, v36
	v_mul_f32_e32 v36, 0x3fb8aa3b, v36
	v_add_f32_e32 v35, v120, v35
	v_exp_f32_e32 v123, v36
	v_add_f32_e32 v36, v46, v35
	v_mul_f32_e32 v36, 0x3fb8aa3b, v36
	v_add_f32_e32 v35, v122, v35
	v_exp_f32_e32 v120, v36
	v_add_f32_e32 v36, v45, v35
	v_add_f32_e32 v35, v121, v35
	v_add_f32_e32 v35, v44, v35
	v_mul_f32_e32 v35, 0x3fb8aa3b, v35
	v_mul_f32_e32 v36, 0x3fb8aa3b, v36
	v_exp_f32_e32 v121, v35
	v_add_f32_e32 v35, v47, v81
	v_exp_f32_e32 v46, v36
	v_add_f32_e32 v35, v63, v35
	v_cndmask_b32_e64 v36, 0, v84, s[52:53]
	v_add_f32_e32 v36, v36, v35
	v_add_f32_e32 v43, v43, v36
	v_add_f32_e32 v36, v109, v36
	v_add_f32_e32 v42, v42, v36
	v_add_f32_e32 v36, v41, v36
	v_add_f32_e32 v40, v40, v36
	v_add_f32_e32 v36, v39, v36
	v_add_f32_e32 v36, v38, v36
	v_mul_f32_e32 v36, 0x3fb8aa3b, v36
	v_add_f32_e32 v63, v37, v84
	v_exp_f32_e32 v81, v36
	v_pk_add_f32 v[36:37], v[62:63], v[34:35]
	v_pk_add_f32 v[38:39], v[60:61], v[32:33]
	v_mul_f32_e32 v40, 0x3fb8aa3b, v40
	v_pk_add_f32 v[38:39], v[38:39], v[36:37]
	v_exp_f32_e32 v44, v40
	v_cndmask_b32_e64 v40, 0, v33, s[52:53]
	ds_bpermute_b32 v33, v110, v38
	v_add_f32_e32 v35, v40, v37
	v_add_f32_e32 v36, v108, v35
	v_add_f32_e32 v35, v107, v35
	v_mul_f32_e32 v42, 0x3fb8aa3b, v42
	s_waitcnt lgkmcnt(0)
	v_cndmask_b32_e64 v41, 0, v33, s[52:53]
	v_add_f32_e32 v41, v41, v39
	v_add_f32_e32 v37, v106, v35
	v_add_f32_e32 v35, v105, v35
	v_add_f32_e32 v34, v34, v41
	v_exp_f32_e32 v47, v42
	v_add_f32_e32 v40, v103, v35
	v_add_f32_e32 v35, v99, v35
	v_add_f32_e32 v42, v86, v41
	v_add_f32_e32 v41, v85, v34
	v_add_f32_e32 v34, v62, v34
	v_mul_f32_e32 v43, 0x3fb8aa3b, v43
	v_add_f32_e32 v35, v87, v35
	v_add_f32_e32 v32, v32, v34
	v_exp_f32_e32 v45, v43
	v_mul_f32_e32 v40, 0x3fb8aa3b, v40
	v_mul_f32_e32 v35, 0x3fb8aa3b, v35
	v_mul_f32_e32 v42, 0x3fb8aa3b, v42
	v_mul_f32_e32 v41, 0x3fb8aa3b, v41
	v_add_f32_e32 v43, v83, v34
	v_add_f32_e32 v32, v82, v32
	v_mul_f32_e32 v36, 0x3fb8aa3b, v36
	v_mul_f32_e32 v37, 0x3fb8aa3b, v37
	v_exp_f32_e32 v40, v40
	v_exp_f32_e32 v35, v35
	v_exp_f32_e32 v42, v42
	v_mul_f32_e32 v43, 0x3fb8aa3b, v43
	v_mul_f32_e32 v32, 0x3fb8aa3b, v32
	v_exp_f32_e32 v34, v41
	v_exp_f32_e32 v36, v36
	v_exp_f32_e32 v37, v37
	v_exp_f32_e32 v43, v43
	v_exp_f32_e32 v32, v32
	v_add_f32_e32 v33, v38, v33
	v_add_f32_e32 v63, v33, v39
	v_cvt_pk_bf16_f32 v33, v34, v42
	v_cvt_pk_bf16_f32 v34, v35, v40
	v_add_u32_e32 v40, 0x2000, v80
	v_cvt_pk_bf16_f32 v32, v32, v43
	v_cvt_pk_bf16_f32 v35, v37, v36
	ds_read2_b64 v[36:39], v40 offset0:128 offset1:130
	ds_read2_b64 v[40:43], v40 offset0:132 offset1:134
	v_cvt_pk_bf16_f32 v44, v81, v44
	v_cvt_pk_bf16_f32 v45, v47, v45
	v_cvt_pk_bf16_f32 v46, v121, v46
	v_cvt_pk_bf16_f32 v47, v120, v123
	s_setprio 1
	s_waitcnt lgkmcnt(0)
	v_mfma_f32_32x32x16_bf16 v[16:31], v[36:39], v[32:35], v[16:31]
	v_mfma_f32_32x32x16_bf16 v[16:31], v[40:43], v[44:47], v[16:31]
	s_setprio 0
	v_add_u32_e32 v40, 0x3000, v80
	ds_read2_b64 v[36:39], v40 offset0:160 offset1:162
	ds_read2_b64 v[40:43], v40 offset0:164 offset1:166
	s_setprio 1
	s_waitcnt lgkmcnt(0)
	v_mfma_f32_32x32x16_bf16 v[0:15], v[36:39], v[32:35], v[0:15]
	v_mfma_f32_32x32x16_bf16 v[0:15], v[40:43], v[44:47], v[0:15]
	s_setprio 0
	v_cmp_gt_f32_e32 vcc, s5, v63
	s_cmp_lg_u64 vcc, exec
	s_cselect_b64 s[14:15], -1, 0
